# v35 + s_setprio 1 around the scan prepare half-step
# baseline (speedup 1.0000x reference)
.LBB0_1184:
	s_and_b64 vcc, exec, s[14:15]
	s_cbranch_vccz .LBB0_1176
	s_setprio 1
	s_waitcnt vmcnt(0)
	v_cvt_f32_f16_sdwa v81, v170 dst_sel:DWORD dst_unused:UNUSED_PAD src0_sel:WORD_1
	v_cvt_f32_f16_e32 v80, v170
	v_cvt_f32_f16_sdwa v83, v172 dst_sel:DWORD dst_unused:UNUSED_PAD src0_sel:WORD_1
	v_cvt_f32_f16_e32 v82, v172
	v_cvt_f32_f16_sdwa v85, v174 dst_sel:DWORD dst_unused:UNUSED_PAD src0_sel:WORD_1
	v_cvt_f32_f16_e32 v84, v174
	v_cvt_f32_f16_sdwa v87, v176 dst_sel:DWORD dst_unused:UNUSED_PAD src0_sel:WORD_1
	v_cvt_f32_f16_e32 v86, v176
	v_pk_add_f32 v[88:89], v[80:81], 0 op_sel_hi:[1,0]
	v_cvt_f32_f16_sdwa v97, v178 dst_sel:DWORD dst_unused:UNUSED_PAD src0_sel:WORD_1
	v_cvt_f32_f16_e32 v96, v178
	v_pk_add_f32 v[90:91], v[88:89], v[82:83]
	v_cvt_f32_f16_sdwa v99, v182 dst_sel:DWORD dst_unused:UNUSED_PAD src0_sel:WORD_1
	v_cvt_f32_f16_e32 v98, v182
	v_pk_add_f32 v[92:93], v[90:91], v[84:85]
	v_cvt_f32_f16_sdwa v75, v184 dst_sel:DWORD dst_unused:UNUSED_PAD src0_sel:WORD_1
	v_cvt_f32_f16_e32 v74, v184
	v_pk_add_f32 v[94:95], v[92:93], v[86:87]
	v_cvt_f32_f16_sdwa v69, v199 dst_sel:DWORD dst_unused:UNUSED_PAD src0_sel:WORD_1
	v_cvt_f32_f16_e32 v68, v199
	v_pk_add_f32 v[100:101], v[94:95], v[96:97]
	v_exp_f32_e32 v80, v80
	v_pk_add_f32 v[102:103], v[100:101], v[98:99]
	v_exp_f32_e32 v81, v81
	v_pk_add_f32 v[104:105], v[102:103], v[74:75]
	ds_write_b128 v190, v[136:139] offset:36096
	ds_write_b128 v190, v[132:135] offset:36112
	v_pk_add_f32 v[72:73], v[104:105], v[68:69]
	ds_bpermute_b32 v70, v200, v72
	ds_bpermute_b32 v71, v200, v73
	ds_bpermute_b32 v76, v200, v72 offset:64
	ds_bpermute_b32 v77, v200, v73 offset:64
	ds_bpermute_b32 v78, v200, v72 offset:128
	ds_bpermute_b32 v79, v200, v73 offset:128
	ds_bpermute_b32 v106, v200, v72 offset:192
	ds_bpermute_b32 v107, v200, v73 offset:192
	s_waitcnt lgkmcnt(6)
	v_cndmask_b32_e64 v109, 0, v71, s[6:7]
	v_cndmask_b32_e64 v108, 0, v70, s[6:7]
	s_waitcnt lgkmcnt(4)
	v_cndmask_b32_e64 v111, 0, v77, s[8:9]
	v_cndmask_b32_e64 v110, 0, v76, s[8:9]
	v_pk_add_f32 v[108:109], v[108:109], v[110:111]
	s_waitcnt lgkmcnt(2)
	v_cndmask_b32_e64 v111, 0, v79, s[10:11]
	v_cndmask_b32_e64 v110, 0, v78, s[10:11]
	v_pk_add_f32 v[108:109], v[108:109], v[110:111]
	v_pk_add_f32 v[110:111], v[70:71], v[76:77]
	v_pk_add_f32 v[80:81], v[80:81], 1.0 op_sel_hi:[1,0] neg_lo:[1,0] neg_hi:[1,0]
	v_pk_add_f32 v[70:71], v[110:111], v[78:79]
	v_exp_f32_e32 v76, v110
	s_waitcnt lgkmcnt(0)
	v_pk_add_f32 v[70:71], v[70:71], v[106:107]
	v_pk_add_f32 v[106:107], v[108:109], v[110:111] neg_lo:[0,1] neg_hi:[0,1]
	v_exp_f32_e32 v77, v111
	v_pk_add_f32 v[88:89], v[88:89], v[106:107]
	v_pk_add_f32 v[78:79], v[70:71], v[110:111] neg_lo:[0,1] neg_hi:[0,1]
	v_exp_f32_e32 v108, v88
	v_exp_f32_e32 v109, v89
	v_exp_f32_e64 v88, -v88
	v_exp_f32_e64 v89, -v89
	v_exp_f32_e32 v78, v78
	v_exp_f32_e32 v79, v79
	v_lshlrev_b32_e32 v110, 16, v169
	v_and_b32_e32 v111, 0xffff0000, v169
	v_pk_mul_f32 v[108:109], v[108:109], v[110:111]
	v_pk_mul_f32 v[80:81], v[80:81], v[88:89]
	v_pk_mul_f32 v[88:89], v[76:77], v[108:109]
	v_pk_mul_f32 v[110:111], v[78:79], v[80:81]
	v_cvt_pk_bf16_f32 v108, v108, v109
	v_cvt_pk_bf16_f32 v88, v88, v89
	v_cvt_pk_bf16_f32 v80, v80, v81
	ds_write_b32 v191, v108
	ds_write_b32 v192, v88 offset:8704
	ds_write_b32 v191, v80 offset:17152
	v_cvt_pk_bf16_f32 v80, v110, v111
	ds_write_b32 v193, v80 offset:25856
	v_pk_add_f32 v[80:81], v[90:91], v[106:107]
	v_exp_f32_e32 v82, v82
	v_exp_f32_e32 v83, v83
	v_exp_f32_e32 v88, v80
	v_exp_f32_e32 v89, v81
	v_exp_f32_e64 v80, -v80
	v_exp_f32_e64 v81, -v81
	v_pk_add_f32 v[82:83], v[82:83], 1.0 op_sel_hi:[1,0] neg_lo:[1,0] neg_hi:[1,0]
	v_lshlrev_b32_e32 v90, 16, v171
	v_and_b32_e32 v91, 0xffff0000, v171
	v_pk_mul_f32 v[88:89], v[88:89], v[90:91]
	v_pk_mul_f32 v[80:81], v[82:83], v[80:81]
	v_pk_mul_f32 v[82:83], v[76:77], v[88:89]
	v_pk_mul_f32 v[90:91], v[78:79], v[80:81]
	v_cvt_pk_bf16_f32 v88, v88, v89
	v_cvt_pk_bf16_f32 v80, v80, v81
	v_cvt_pk_bf16_f32 v82, v82, v83
	ds_write2st64_b32 v195, v88, v80 offset1:67
	v_cvt_pk_bf16_f32 v80, v90, v91
	ds_write_b32 v196, v82 offset:8704
	ds_write_b32 v197, v80 offset:25856
	v_pk_add_f32 v[80:81], v[92:93], v[106:107]
	v_exp_f32_e32 v84, v84
	v_exp_f32_e32 v82, v80
	v_exp_f32_e32 v85, v85
	v_exp_f32_e32 v83, v81
	v_exp_f32_e64 v80, -v80
	v_exp_f32_e64 v81, -v81
	v_lshlrev_b32_e32 v88, 16, v173
	v_and_b32_e32 v89, 0xffff0000, v173
	v_pk_add_f32 v[84:85], v[84:85], 1.0 op_sel_hi:[1,0] neg_lo:[1,0] neg_hi:[1,0]
	v_pk_mul_f32 v[82:83], v[82:83], v[88:89]
	v_pk_mul_f32 v[80:81], v[84:85], v[80:81]
	v_pk_mul_f32 v[84:85], v[76:77], v[82:83]
	v_pk_mul_f32 v[88:89], v[78:79], v[80:81]
	v_cvt_pk_bf16_f32 v91, v84, v85
	v_cvt_pk_bf16_f32 v92, v80, v81
	v_pk_add_f32 v[80:81], v[94:95], v[106:107]
	v_exp_f32_e32 v84, v86
	v_exp_f32_e32 v85, v87
	v_cvt_pk_bf16_f32 v90, v82, v83
	v_exp_f32_e32 v82, v80
	v_exp_f32_e32 v83, v81
	v_exp_f32_e64 v80, -v80
	v_exp_f32_e64 v81, -v81
	v_pk_add_f32 v[84:85], v[84:85], 1.0 op_sel_hi:[1,0] neg_lo:[1,0] neg_hi:[1,0]
	v_lshlrev_b32_e32 v86, 16, v175
	v_and_b32_e32 v87, 0xffff0000, v175
	v_pk_mul_f32 v[82:83], v[82:83], v[86:87]
	v_pk_mul_f32 v[80:81], v[84:85], v[80:81]
	v_cvt_pk_bf16_f32 v88, v88, v89
	v_pk_mul_f32 v[84:85], v[76:77], v[82:83]
	v_pk_mul_f32 v[86:87], v[78:79], v[80:81]
	v_cvt_pk_bf16_f32 v82, v82, v83
	v_cvt_pk_bf16_f32 v80, v80, v81
	v_add_u32_e32 v89, 0x4400, v195
	ds_write2_b32 v195, v90, v82 offset0:68 offset1:136
	v_cvt_pk_bf16_f32 v82, v84, v85
	v_add_u32_e32 v83, 0x2200, v196
	ds_write2_b32 v89, v92, v80 offset0:4 offset1:72
	v_cvt_pk_bf16_f32 v80, v86, v87
	v_add_u32_e32 v81, 0x6400, v197
	ds_write2_b32 v83, v91, v82 offset0:66 offset1:132
	ds_write2_b32 v81, v88, v80 offset0:144 offset1:224
	v_pk_add_f32 v[80:81], v[100:101], v[106:107]
	v_exp_f32_e32 v84, v96
	v_exp_f32_e32 v82, v80
	v_exp_f32_e32 v85, v97
	v_exp_f32_e32 v83, v81
	v_exp_f32_e64 v80, -v80
	v_exp_f32_e64 v81, -v81
	v_lshlrev_b32_e32 v86, 16, v177
	v_and_b32_e32 v87, 0xffff0000, v177
	v_pk_add_f32 v[84:85], v[84:85], 1.0 op_sel_hi:[1,0] neg_lo:[1,0] neg_hi:[1,0]
	v_pk_mul_f32 v[82:83], v[82:83], v[86:87]
	v_pk_mul_f32 v[80:81], v[84:85], v[80:81]
	v_pk_mul_f32 v[84:85], v[76:77], v[82:83]
	v_pk_mul_f32 v[86:87], v[78:79], v[80:81]
	v_cvt_pk_bf16_f32 v90, v84, v85
	v_cvt_pk_bf16_f32 v91, v80, v81
	v_pk_add_f32 v[80:81], v[102:103], v[106:107]
	v_exp_f32_e32 v84, v98
	v_exp_f32_e32 v85, v99
	v_cvt_pk_bf16_f32 v88, v82, v83
	v_exp_f32_e32 v82, v80
	v_exp_f32_e32 v83, v81
	v_exp_f32_e64 v80, -v80
	v_exp_f32_e64 v81, -v81
	v_cvt_pk_bf16_f32 v92, v86, v87
	v_pk_add_f32 v[84:85], v[84:85], 1.0 op_sel_hi:[1,0] neg_lo:[1,0] neg_hi:[1,0]
	v_lshlrev_b32_e32 v86, 16, v181
	v_and_b32_e32 v87, 0xffff0000, v181
	v_pk_mul_f32 v[82:83], v[82:83], v[86:87]
	v_pk_mul_f32 v[80:81], v[84:85], v[80:81]
	v_pk_mul_f32 v[84:85], v[76:77], v[82:83]
	v_pk_mul_f32 v[86:87], v[78:79], v[80:81]
	v_cvt_pk_bf16_f32 v82, v82, v83
	v_add_u32_e32 v83, 0x200, v195
	v_cvt_pk_bf16_f32 v80, v80, v81
	ds_write2_b32 v83, v88, v82 offset0:76 offset1:144
	v_cvt_pk_bf16_f32 v82, v84, v85
	v_add_u32_e32 v83, 0x2400, v196
	ds_write2_b32 v89, v91, v80 offset0:140 offset1:208
	v_cvt_pk_bf16_f32 v80, v86, v87
	v_add_u32_e32 v81, 0x6800, v197
	ds_write2_b32 v83, v90, v82 offset0:70 offset1:136
	ds_write2_b32 v81, v92, v80 offset0:48 offset1:128
	v_pk_add_f32 v[80:81], v[104:105], v[106:107]
	v_exp_f32_e32 v74, v74
	v_exp_f32_e32 v75, v75
	v_exp_f32_e32 v82, v80
	v_exp_f32_e32 v83, v81
	v_exp_f32_e64 v80, -v80
	v_exp_f32_e64 v81, -v81
	v_pk_add_f32 v[74:75], v[74:75], 1.0 op_sel_hi:[1,0] neg_lo:[1,0] neg_hi:[1,0]
	v_lshlrev_b32_e32 v84, 16, v183
	v_and_b32_e32 v85, 0xffff0000, v183
	v_pk_mul_f32 v[82:83], v[82:83], v[84:85]
	v_pk_mul_f32 v[74:75], v[74:75], v[80:81]
	v_pk_add_f32 v[72:73], v[72:73], v[106:107]
	v_exp_f32_e32 v68, v68
	v_exp_f32_e32 v69, v69
	v_pk_mul_f32 v[80:81], v[76:77], v[82:83]
	v_pk_mul_f32 v[84:85], v[78:79], v[74:75]
	v_cvt_pk_bf16_f32 v82, v82, v83
	v_cvt_pk_bf16_f32 v83, v74, v75
	v_exp_f32_e32 v74, v72
	v_exp_f32_e32 v75, v73
	v_exp_f32_e64 v72, -v72
	v_exp_f32_e64 v73, -v73
	v_cvt_pk_bf16_f32 v80, v80, v81
	ds_write_b32 v196, v80 offset:10024
	v_pk_add_f32 v[68:69], v[68:69], 1.0 op_sel_hi:[1,0] neg_lo:[1,0] neg_hi:[1,0]
	v_lshlrev_b32_e32 v80, 16, v194
	v_and_b32_e32 v81, 0xffff0000, v194
	v_pk_mul_f32 v[74:75], v[74:75], v[80:81]
	v_pk_mul_f32 v[68:69], v[68:69], v[72:73]
	v_pk_mul_f32 v[72:73], v[76:77], v[74:75]
	v_pk_mul_f32 v[76:77], v[78:79], v[68:69]
	v_cvt_pk_bf16_f32 v68, v68, v69
	v_add_u32_e32 v69, 0x4800, v195
	v_cvt_pk_bf16_f32 v84, v84, v85
	v_cvt_pk_bf16_f32 v74, v74, v75
	v_add_u32_e32 v75, 0x400, v195
	v_cvt_pk_bf16_f32 v72, v72, v73
	ds_write2_b32 v69, v83, v68 offset0:20 offset1:88
	v_cvt_pk_bf16_f32 v68, v76, v77
	v_add_u32_e32 v69, 0x6a00, v197
	ds_write2_b32 v75, v82, v74 offset0:84 offset1:152
	ds_write_b32 v196, v72 offset:10288
	ds_write2_b32 v69, v84, v68 offset0:80 offset1:160
	s_and_saveexec_b64 s[14:15], s[12:13]
	s_cbranch_execz .LBB0_1187
	v_exp_f32_e32 v68, v70
	v_exp_f32_e32 v69, v71
	ds_write_b64 v198, v[68:69] offset:46336

.LBB0_1341:
	s_and_b64 vcc, exec, s[14:15]
	s_cbranch_vccz .LBB0_1333
	s_setprio 1
	s_waitcnt vmcnt(16)
	v_cvt_f32_f16_sdwa v79, v184 dst_sel:DWORD dst_unused:UNUSED_PAD src0_sel:WORD_1
	v_cvt_f32_f16_e32 v78, v184
	s_waitcnt vmcnt(14)
	v_cvt_f32_f16_sdwa v81, v186 dst_sel:DWORD dst_unused:UNUSED_PAD src0_sel:WORD_1
	v_cvt_f32_f16_e32 v80, v186
	s_waitcnt vmcnt(12)
	v_cvt_f32_f16_sdwa v83, v188 dst_sel:DWORD dst_unused:UNUSED_PAD src0_sel:WORD_1
	v_cvt_f32_f16_e32 v82, v188
	s_waitcnt vmcnt(10)
	v_cvt_f32_f16_sdwa v85, v190 dst_sel:DWORD dst_unused:UNUSED_PAD src0_sel:WORD_1
	v_cvt_f32_f16_e32 v84, v190
	v_pk_add_f32 v[86:87], v[78:79], 0 op_sel_hi:[1,0]
	s_waitcnt vmcnt(8)
	v_cvt_f32_f16_sdwa v95, v193 dst_sel:DWORD dst_unused:UNUSED_PAD src0_sel:WORD_1
	v_cvt_f32_f16_e32 v94, v193
	v_pk_add_f32 v[88:89], v[86:87], v[80:81]
	s_waitcnt vmcnt(6)
	v_cvt_f32_f16_sdwa v97, v198 dst_sel:DWORD dst_unused:UNUSED_PAD src0_sel:WORD_1
	v_cvt_f32_f16_e32 v96, v198
	v_pk_add_f32 v[90:91], v[88:89], v[82:83]
	s_waitcnt vmcnt(4)
	v_cvt_f32_f16_sdwa v73, v201 dst_sel:DWORD dst_unused:UNUSED_PAD src0_sel:WORD_1
	v_cvt_f32_f16_e32 v72, v201
	v_pk_add_f32 v[92:93], v[90:91], v[84:85]
	s_waitcnt vmcnt(2)
	v_cvt_f32_f16_sdwa v67, v216 dst_sel:DWORD dst_unused:UNUSED_PAD src0_sel:WORD_1
	v_cvt_f32_f16_e32 v66, v216
	v_pk_add_f32 v[98:99], v[92:93], v[94:95]
	v_and_or_b32 v68, v169, 64, v153
	v_pk_add_f32 v[100:101], v[98:99], v[96:97]
	v_lshlrev_b32_e32 v105, 2, v68
	v_pk_add_f32 v[102:103], v[100:101], v[72:73]
	v_exp_f32_e32 v78, v78
	v_pk_add_f32 v[70:71], v[102:103], v[66:67]
	ds_bpermute_b32 v68, v105, v70
	ds_bpermute_b32 v69, v105, v71
	ds_bpermute_b32 v74, v105, v70 offset:64
	ds_bpermute_b32 v75, v105, v71 offset:64
	ds_bpermute_b32 v76, v105, v70 offset:128
	ds_bpermute_b32 v77, v105, v71 offset:128
	ds_bpermute_b32 v104, v105, v70 offset:192
	ds_bpermute_b32 v105, v105, v71 offset:192
	s_waitcnt lgkmcnt(6)
	v_cndmask_b32_e64 v107, 0, v69, s[6:7]
	v_cndmask_b32_e64 v106, 0, v68, s[6:7]
	s_waitcnt lgkmcnt(4)
	v_cndmask_b32_e64 v109, 0, v75, s[8:9]
	v_cndmask_b32_e64 v108, 0, v74, s[8:9]
	v_pk_add_f32 v[106:107], v[106:107], v[108:109]
	s_waitcnt lgkmcnt(2)
	v_cndmask_b32_e64 v109, 0, v77, s[10:11]
	v_cndmask_b32_e64 v108, 0, v76, s[10:11]
	v_pk_add_f32 v[106:107], v[106:107], v[108:109]
	v_pk_add_f32 v[108:109], v[68:69], v[74:75]
	v_exp_f32_e32 v79, v79
	v_pk_add_f32 v[68:69], v[108:109], v[76:77]
	v_exp_f32_e32 v74, v108
	s_waitcnt lgkmcnt(0)
	v_pk_add_f32 v[68:69], v[68:69], v[104:105]
	v_pk_add_f32 v[104:105], v[106:107], v[108:109] neg_lo:[0,1] neg_hi:[0,1]
	v_exp_f32_e32 v75, v109
	v_pk_add_f32 v[86:87], v[86:87], v[104:105]
	v_pk_add_f32 v[76:77], v[68:69], v[108:109] neg_lo:[0,1] neg_hi:[0,1]
	v_exp_f32_e32 v106, v86
	v_exp_f32_e32 v107, v87
	v_exp_f32_e64 v86, -v86
	v_exp_f32_e64 v87, -v87
	v_exp_f32_e32 v76, v76
	v_exp_f32_e32 v77, v77
	v_lshlrev_b32_e32 v108, 16, v183
	v_and_b32_e32 v109, 0xffff0000, v183
	v_pk_add_f32 v[78:79], v[78:79], 1.0 op_sel_hi:[1,0] neg_lo:[1,0] neg_hi:[1,0]
	v_pk_mul_f32 v[106:107], v[106:107], v[108:109]
	v_pk_mul_f32 v[78:79], v[78:79], v[86:87]
	v_pk_mul_f32 v[86:87], v[74:75], v[106:107]
	v_pk_mul_f32 v[108:109], v[76:77], v[78:79]
	v_cvt_pk_bf16_f32 v106, v106, v107
	v_cvt_pk_bf16_f32 v86, v86, v87
	v_cvt_pk_bf16_f32 v78, v78, v79
	s_waitcnt vmcnt(0)
	ds_write_b128 v207, v[134:137] offset:36096
	ds_write_b128 v207, v[130:133] offset:36112
	ds_write_b32 v208, v106
	ds_write_b32 v209, v86 offset:8704
	ds_write_b32 v208, v78 offset:17152
	v_cvt_pk_bf16_f32 v78, v108, v109
	ds_write_b32 v210, v78 offset:25856
	v_pk_add_f32 v[78:79], v[88:89], v[104:105]
	v_exp_f32_e32 v80, v80
	v_exp_f32_e32 v81, v81
	v_exp_f32_e32 v86, v78
	v_exp_f32_e32 v87, v79
	v_exp_f32_e64 v78, -v78
	v_exp_f32_e64 v79, -v79
	v_pk_add_f32 v[80:81], v[80:81], 1.0 op_sel_hi:[1,0] neg_lo:[1,0] neg_hi:[1,0]
	v_lshlrev_b32_e32 v88, 16, v185
	v_and_b32_e32 v89, 0xffff0000, v185
	v_pk_mul_f32 v[86:87], v[86:87], v[88:89]
	v_pk_mul_f32 v[78:79], v[80:81], v[78:79]
	v_pk_mul_f32 v[80:81], v[74:75], v[86:87]
	v_pk_mul_f32 v[88:89], v[76:77], v[78:79]
	v_cvt_pk_bf16_f32 v86, v86, v87
	v_cvt_pk_bf16_f32 v78, v78, v79
	v_cvt_pk_bf16_f32 v80, v80, v81
	ds_write2st64_b32 v211, v86, v78 offset1:67
	v_cvt_pk_bf16_f32 v78, v88, v89
	ds_write_b32 v212, v80 offset:8704
	ds_write_b32 v213, v78 offset:25856
	v_pk_add_f32 v[78:79], v[90:91], v[104:105]
	v_exp_f32_e32 v82, v82
	v_exp_f32_e32 v80, v78
	v_exp_f32_e32 v83, v83
	v_exp_f32_e32 v81, v79
	v_exp_f32_e64 v78, -v78
	v_exp_f32_e64 v79, -v79
	v_lshlrev_b32_e32 v86, 16, v187
	v_and_b32_e32 v87, 0xffff0000, v187
	v_pk_add_f32 v[82:83], v[82:83], 1.0 op_sel_hi:[1,0] neg_lo:[1,0] neg_hi:[1,0]
	v_pk_mul_f32 v[80:81], v[80:81], v[86:87]
	v_pk_mul_f32 v[78:79], v[82:83], v[78:79]
	v_pk_mul_f32 v[82:83], v[74:75], v[80:81]
	v_pk_mul_f32 v[86:87], v[76:77], v[78:79]
	v_cvt_pk_bf16_f32 v89, v82, v83
	v_cvt_pk_bf16_f32 v90, v78, v79
	v_pk_add_f32 v[78:79], v[92:93], v[104:105]
	v_exp_f32_e32 v82, v84
	v_exp_f32_e32 v83, v85
	v_cvt_pk_bf16_f32 v88, v80, v81
	v_exp_f32_e32 v80, v78
	v_exp_f32_e32 v81, v79
	v_exp_f32_e64 v78, -v78
	v_exp_f32_e64 v79, -v79
	v_pk_add_f32 v[82:83], v[82:83], 1.0 op_sel_hi:[1,0] neg_lo:[1,0] neg_hi:[1,0]
	v_lshlrev_b32_e32 v84, 16, v189
	v_and_b32_e32 v85, 0xffff0000, v189
	v_pk_mul_f32 v[80:81], v[80:81], v[84:85]
	v_pk_mul_f32 v[78:79], v[82:83], v[78:79]
	v_cvt_pk_bf16_f32 v86, v86, v87
	v_pk_mul_f32 v[82:83], v[74:75], v[80:81]
	v_pk_mul_f32 v[84:85], v[76:77], v[78:79]
	v_cvt_pk_bf16_f32 v80, v80, v81
	v_cvt_pk_bf16_f32 v78, v78, v79
	v_add_u32_e32 v87, 0x4400, v211
	ds_write2_b32 v211, v88, v80 offset0:68 offset1:136
	v_cvt_pk_bf16_f32 v80, v82, v83
	v_add_u32_e32 v81, 0x2200, v212
	ds_write2_b32 v87, v90, v78 offset0:4 offset1:72
	v_cvt_pk_bf16_f32 v78, v84, v85
	v_add_u32_e32 v79, 0x6400, v213
	ds_write2_b32 v81, v89, v80 offset0:66 offset1:132
	ds_write2_b32 v79, v86, v78 offset0:144 offset1:224
	v_pk_add_f32 v[78:79], v[98:99], v[104:105]
	v_exp_f32_e32 v82, v94
	v_exp_f32_e32 v80, v78
	v_exp_f32_e32 v83, v95
	v_exp_f32_e32 v81, v79
	v_exp_f32_e64 v78, -v78
	v_exp_f32_e64 v79, -v79
	v_lshlrev_b32_e32 v84, 16, v192
	v_and_b32_e32 v85, 0xffff0000, v192
	v_pk_add_f32 v[82:83], v[82:83], 1.0 op_sel_hi:[1,0] neg_lo:[1,0] neg_hi:[1,0]
	v_pk_mul_f32 v[80:81], v[80:81], v[84:85]
	v_pk_mul_f32 v[78:79], v[82:83], v[78:79]
	v_pk_mul_f32 v[82:83], v[74:75], v[80:81]
	v_pk_mul_f32 v[84:85], v[76:77], v[78:79]
	v_cvt_pk_bf16_f32 v88, v82, v83
	v_cvt_pk_bf16_f32 v89, v78, v79
	v_pk_add_f32 v[78:79], v[100:101], v[104:105]
	v_exp_f32_e32 v82, v96
	v_exp_f32_e32 v83, v97
	v_cvt_pk_bf16_f32 v86, v80, v81
	v_exp_f32_e32 v80, v78
	v_exp_f32_e32 v81, v79
	v_exp_f32_e64 v78, -v78
	v_exp_f32_e64 v79, -v79
	v_cvt_pk_bf16_f32 v90, v84, v85
	v_pk_add_f32 v[82:83], v[82:83], 1.0 op_sel_hi:[1,0] neg_lo:[1,0] neg_hi:[1,0]
	v_lshlrev_b32_e32 v84, 16, v197
	v_and_b32_e32 v85, 0xffff0000, v197
	v_pk_mul_f32 v[80:81], v[80:81], v[84:85]
	v_pk_mul_f32 v[78:79], v[82:83], v[78:79]
	v_pk_mul_f32 v[82:83], v[74:75], v[80:81]
	v_pk_mul_f32 v[84:85], v[76:77], v[78:79]
	v_cvt_pk_bf16_f32 v80, v80, v81
	v_add_u32_e32 v81, 0x200, v211
	v_cvt_pk_bf16_f32 v78, v78, v79
	ds_write2_b32 v81, v86, v80 offset0:76 offset1:144
	v_cvt_pk_bf16_f32 v80, v82, v83
	v_add_u32_e32 v81, 0x2400, v212
	ds_write2_b32 v87, v89, v78 offset0:140 offset1:208
	v_cvt_pk_bf16_f32 v78, v84, v85
	v_add_u32_e32 v79, 0x6800, v213
	ds_write2_b32 v81, v88, v80 offset0:70 offset1:136
	ds_write2_b32 v79, v90, v78 offset0:48 offset1:128
	v_pk_add_f32 v[78:79], v[102:103], v[104:105]
	v_exp_f32_e32 v72, v72
	v_exp_f32_e32 v73, v73
	v_exp_f32_e32 v80, v78
	v_exp_f32_e32 v81, v79
	v_exp_f32_e64 v78, -v78
	v_exp_f32_e64 v79, -v79
	v_pk_add_f32 v[72:73], v[72:73], 1.0 op_sel_hi:[1,0] neg_lo:[1,0] neg_hi:[1,0]
	v_lshlrev_b32_e32 v82, 16, v200
	v_and_b32_e32 v83, 0xffff0000, v200
	v_pk_mul_f32 v[80:81], v[80:81], v[82:83]
	v_pk_mul_f32 v[72:73], v[72:73], v[78:79]
	v_pk_add_f32 v[70:71], v[70:71], v[104:105]
	v_exp_f32_e32 v66, v66
	v_exp_f32_e32 v67, v67
	v_pk_mul_f32 v[78:79], v[74:75], v[80:81]
	v_pk_mul_f32 v[82:83], v[76:77], v[72:73]
	v_cvt_pk_bf16_f32 v80, v80, v81
	v_cvt_pk_bf16_f32 v81, v72, v73
	v_exp_f32_e32 v72, v70
	v_exp_f32_e32 v73, v71
	v_exp_f32_e64 v70, -v70
	v_exp_f32_e64 v71, -v71
	v_cvt_pk_bf16_f32 v78, v78, v79
	ds_write_b32 v212, v78 offset:10024
	v_pk_add_f32 v[66:67], v[66:67], 1.0 op_sel_hi:[1,0] neg_lo:[1,0] neg_hi:[1,0]
	v_lshlrev_b32_e32 v78, 16, v214
	v_and_b32_e32 v79, 0xffff0000, v214
	v_pk_mul_f32 v[72:73], v[72:73], v[78:79]
	v_pk_mul_f32 v[66:67], v[66:67], v[70:71]
	v_pk_mul_f32 v[70:71], v[74:75], v[72:73]
	v_pk_mul_f32 v[74:75], v[76:77], v[66:67]
	v_cvt_pk_bf16_f32 v66, v66, v67
	v_add_u32_e32 v67, 0x4800, v211
	v_cvt_pk_bf16_f32 v82, v82, v83
	v_cvt_pk_bf16_f32 v72, v72, v73
	v_add_u32_e32 v73, 0x400, v211
	v_cvt_pk_bf16_f32 v70, v70, v71
	ds_write2_b32 v67, v81, v66 offset0:20 offset1:88
	v_cvt_pk_bf16_f32 v66, v74, v75
	v_add_u32_e32 v67, 0x6a00, v213
	ds_write2_b32 v73, v80, v72 offset0:84 offset1:152
	ds_write_b32 v212, v70 offset:10288
	ds_write2_b32 v67, v82, v66 offset0:80 offset1:160
	s_and_saveexec_b64 s[14:15], s[12:13]
	s_cbranch_execz .LBB0_1344
	v_exp_f32_e32 v66, v68
	v_exp_f32_e32 v67, v69
	ds_write_b64 v215, v[66:67] offset:46336
